# swiglu epilogue: row rstd factors cached per row panel in v226-v241 (recomputed only when pm changes), no vmcnt wait in epilogue
# speedup vs baseline: 1.0425x; 1.0224x over previous
; #define PG8_STAGE(bufoff, gbase, voff) do { _Pragma("unroll") for (int _i = 0; _i < 2; ++_i) \
;         __builtin_amdgcn_global_load_lds((const unsigned*)((const char*)(gbase) + (voff)[_i]), (PG8_LAS unsigned*)(lds + (bufoff) + ldsw + _i * 8192), 16, 0, 0); } while (0)
;     __host__ __device__ bool next(int i, Unit& u) const {
;         const long L = (long)i * G + c; if (L >= nwg) return false;
;         int wgid = (int)L; { const int q = nwg / NXCD, r = nwg % NXCD, xcd = wgid % NXCD, off = wgid / NXCD; wgid = (xcd < r ? xcd * (q + 1) : r * (q + 1) + (xcd - r) * q) + off; }
;         const int nig = WGM * nN, gid = wgid / nig, fm = gid * WGM, gsz = (nM - fm) < WGM ? (nM - fm) : WGM;
;         u.pm = fm + ((wgid % nig) % gsz); u.pn = (wgid % nig) / gsz; u.aoff = 0; return true;
; template <class Epi, class Sched, bool ALIGN_EPI = false, bool SP2 = false>
; __device__ __forceinline__ void gemm_phase(PG8_LAS unsigned char* lds, const Gemm g, const Sched& S, const Epi& E) {
;     ...
;     for (int i = 0; i < 2; ++i) { int R, C; stage_rc(tid * 16 + i * 8192, R, C); const int Rb = Epi::PERM ? ((R & ~31) + perm32(R & 31)) : R;
;         voffA[i] = (unsigned)(R * g.lda + C) * 2u; voffB[i] = (unsigned)(Rb * g.ldb + C) * 2u; }
;     constexpr unsigned kstep = (unsigned)(BK * 2);
;     const unsigned hstepA = (unsigned)HALF * g.lda * 2u, hstepB = (unsigned)HALF * g.ldb * 2u;
;     const unsigned tstepA = 2u * hstepA, tstepB = 2u * hstepB;
;     const unsigned ldsw = (unsigned)wid * 1024u;
;     const int aoff = lds_byte(wr * 64 + fr, fq * 8), boff = lds_byte(wc * 32 + fr, fq * 8);
;     ...
;     Unit cur, nxt; int ui = 0;
;     if (!S.next(0, cur)) return;
;     f32x4 acc[2][2][4][2];
; #pragma unroll
;     for (int a = 0; a < 2; ++a)
; #pragma unroll
;         for (int b = 0; b < 2; ++b)
; #pragma unroll
;             for (int m = 0; m < 4; ++m)
; #pragma unroll
;                 for (int n = 0; n < 2; ++n) acc[a][b][m][n] = (f32x4){0.f, 0.f, 0.f, 0.f};
;     bf16x8 At[4][2], B0[2][2], B1[2][2];
;     const char* cA = (const char*)g.A + (size_t)cur.pm * tstepA + cur.aoff; const char* cB = (const char*)g.Bt + (size_t)cur.pn * tstepB;
;     S.a_ready(cur);
;     if constexpr (SP2) {
;         PG8_STAGE(PG8_SB(0, 0), cB, voffB); PG8_STAGE(PG8_SB(0, 1), cB + hstepB, voffB); PG8_STAGE(PG8_SA(0, 0), cA, voffA); PG8_STAGE(PG8_SA(0, 1), cA + hstepA, voffA);
.LBB0_727:
	s_or_b64 exec, exec, s[52:53]
	s_cmpk_lt_i32 s2, 0xb00
	s_cselect_b64 s[52:53], -1, 0
	s_mov_b64 s[8:9], s[92:93]
	v_mov_b32_e32 v8, v167
	s_and_b64 vcc, exec, s[52:53]
	s_waitcnt lgkmcnt(0)
	s_barrier
	s_mov_b32 s98, -1
	s_cbranch_vccz .LBB0_743
	v_lshl_add_u32 v0, v8, 4, s47
	v_add_u32_e32 v1, 0x2000, v0
	v_ashrrev_i32_e32 v2, 31, v1
	v_lshrrev_b32_e32 v2, 22, v2
	v_add_u32_e32 v2, v1, v2
	v_ashrrev_i32_e32 v9, 10, v2
	v_mul_i32_i24_e32 v2, 0x400, v9
	v_sub_u32_e32 v1, v1, v2
	v_lshrrev_b32_e32 v2, 4, v1
	v_bitop3_b32 v1, v2, v1, 32 bitop3:0x6c
	v_ashrrev_i32_e32 v2, 31, v1
	v_lshrrev_b32_e32 v2, 26, v2
	v_add_u32_e32 v2, v1, v2
	v_ashrrev_i32_e32 v10, 6, v2
	v_lshlrev_b32_e32 v3, 3, v9
	v_and_b32_e32 v2, 0xffc0, v2
	v_and_b32_e32 v3, -16, v3
	v_sub_u32_e32 v1, v1, v2
	v_add_u32_e32 v3, v10, v3
	v_lshrrev_b16_e32 v2, 7, v1
	v_and_b32_e32 v4, 3, v10
	s_mov_b32 s4, 0xfffe0
	v_lshrrev_b32_e32 v5, 2, v3
	v_lshlrev_b32_e32 v6, 1, v3
	v_and_b32_e32 v2, 1, v2
	v_and_or_b32 v4, v3, s4, v4
	v_and_b32_e32 v5, 4, v5
	v_and_b32_e32 v6, 24, v6
	v_add_u16_e32 v1, v1, v2
	v_mov_b32_e32 v2, 1
	v_or3_b32 v4, v4, v5, v6
	v_lshlrev_b32_e32 v5, 5, v9
	v_ashrrev_i16_sdwa v1, v2, sext(v1) dst_sel:DWORD dst_unused:UNUSED_PAD src0_sel:DWORD src1_sel:BYTE_0
	v_and_b32_e32 v5, 32, v5
	v_bfe_i32 v11, v1, 0, 16
	v_add_lshl_u32 v1, v5, v11, 1
	v_lshl_add_u32 v128, v4, 12, v1
	v_lshl_add_u32 v130, v3, 12, v1
	v_ashrrev_i32_e32 v1, 31, v0
	v_lshrrev_b32_e32 v1, 22, v1
	v_add_u32_e32 v1, v0, v1
	v_ashrrev_i32_e32 v12, 10, v1
	v_mul_i32_i24_e32 v1, 0x400, v12
	s_load_dwordx2 s[8:9], s[8:9], 0x90
	v_sub_u32_e32 v0, v0, v1
	v_lshrrev_b32_e32 v1, 4, v0
	v_bitop3_b32 v0, v1, v0, 32 bitop3:0x6c
	v_ashrrev_i32_e32 v1, 31, v0
	v_lshrrev_b32_e32 v1, 26, v1
	s_waitcnt lgkmcnt(0)
	s_add_u32 s0, s8, 0xc800000
	v_add_u32_e32 v1, v0, v1
	v_lshlrev_b32_e32 v3, 3, v12
	s_addc_u32 s1, s9, 0
	v_ashrrev_i32_e32 v13, 6, v1
	v_and_b32_e32 v3, -16, v3
	s_add_u32 s3, s8, 0x2800000
	v_add_u32_e32 v3, v13, v3
	v_and_b32_e32 v4, 3, v13
	s_addc_u32 s24, s9, 0
	v_and_or_b32 v4, v3, s4, v4
	s_lshr_b32 s4, s80, 29
	s_add_i32 s4, s2, s4
	s_ashr_i32 s5, s4, 3
	s_and_b32 s4, s4, -8
	s_sub_i32 s4, s2, s4
	s_cmp_lt_i32 s4, 0
	s_movk_i32 s25, 0x161
	s_cselect_b32 s10, s25, 0x160
	s_mul_i32 s4, s4, s10
	s_add_i32 s4, s4, s5
	s_mul_hi_i32 s5, s4, 0x2e8ba2e9
	s_lshr_b32 s10, s5, 31
	s_ashr_i32 s5, s5, 6
	s_add_i32 s5, s5, s10
	s_lshl_b32 s10, s5, 3
	s_mulk_i32 s5, 0x160
	s_sub_i32 s4, s4, s5
	s_sext_i32_i16 s5, s4
	s_bfe_u32 s5, s5, 0x3001c
	s_add_i32 s5, s4, s5
	s_sext_i32_i16 s11, s5
	s_and_b32 s5, s5, 0xfff8
	s_sub_i32 s4, s4, s5
	s_sext_i32_i16 s4, s4
	v_lshrrev_b32_e32 v5, 2, v3
	v_lshlrev_b32_e32 v6, 1, v3
	v_and_b32_e32 v1, 0xc0, v1
	s_lshr_b32 s16, s11, 3
	s_add_i32 s26, s10, s4
	v_and_b32_e32 v5, 4, v5
	v_and_b32_e32 v6, 24, v6
	v_sub_u32_e32 v0, v0, v1
	s_ashr_i32 s27, s26, 31
	s_bfe_i64 s[10:11], s[16:17], 0x100000
	v_or3_b32 v4, v4, v5, v6
	v_lshlrev_b32_e32 v5, 5, v12
	v_ashrrev_i16_sdwa v0, v2, sext(v0) dst_sel:DWORD dst_unused:UNUSED_PAD src0_sel:DWORD src1_sel:BYTE_0
	s_lshl_b64 s[4:5], s[26:27], 20
	s_lshl_b64 s[10:11], s[10:11], 20
	v_and_b32_e32 v5, 32, v5
	v_bfe_i32 v14, v0, 0, 16
	s_add_u32 s30, s3, s10
	v_add_lshl_u32 v0, v5, v14, 1
	s_addc_u32 s31, s24, s11
	s_add_i32 s27, s47, 0
	v_lshl_add_u32 v132, v4, 12, v0
	s_add_i32 m0, s27, 0x10000
	v_lshl_add_u32 v134, v3, 12, v0
	global_load_lds_dwordx4 v132, s[30:31]
	s_add_i32 m0, s27, 0x12000
	s_add_u32 s10, s30, 0x80000
	global_load_lds_dwordx4 v128, s[30:31]
	s_addc_u32 s11, s31, 0
	s_add_i32 m0, s27, 0x14000
	v_mov_b32_e32 v133, 0
	global_load_lds_dwordx4 v132, s[10:11]
	s_add_i32 m0, s27, 0x16000
	s_add_u32 s28, s0, s4
	s_addc_u32 s29, s1, s5
	s_add_i32 s33, s27, 0x2000
	global_load_lds_dwordx4 v128, s[10:11]
	s_mov_b32 m0, s27
	s_add_u32 s4, s28, 0x80000
	global_load_lds_dwordx4 v134, s[28:29]
	s_mov_b32 m0, s33
	s_addc_u32 s5, s29, 0
	s_add_i32 s36, s27, 0x4000
	global_load_lds_dwordx4 v130, s[28:29]
	s_mov_b32 m0, s36
	s_add_i32 s37, s27, 0x6000
	global_load_lds_dwordx4 v134, s[4:5]
	s_mov_b32 m0, s37
	v_mov_b32_e32 v129, v133
	global_load_lds_dwordx4 v130, s[4:5]
	v_mov_b32_e32 v135, v133
	v_mov_b32_e32 v131, v133
	s_mov_b32 s38, 0
	v_lshl_add_u64 v[6:7], s[30:31], 0, v[132:133]
	v_lshl_add_u64 v[4:5], s[30:31], 0, v[128:129]
	v_lshl_add_u64 v[2:3], s[28:29], 0, v[134:135]
	s_and_b64 vcc, exec, s[64:65]
	v_lshl_add_u64 v[0:1], s[28:29], 0, v[130:131]
	s_cbranch_vccnz .LBB0_730
	s_barrier

; __device__ __forceinline__ float shx(float v, int mask, int lane) { return __int_as_float(__builtin_amdgcn_ds_bpermute((lane ^ mask) << 2, __float_as_int(v))); }
; __device__ __forceinline__ float row_rstd(const float* ssqp, int row, int fr, int fq) {
;     const f32x4 p0 = *(const f32x4*)(ssqp + (size_t)row * 32 + fq * 8), p1 = *(const f32x4*)(ssqp + (size_t)row * 32 + fq * 8 + 4);
;     float t = ((p0[0] + p0[1]) + (p0[2] + p0[3])) + ((p1[0] + p1[1]) + (p1[2] + p1[3])); const int ln = fr + 16 * fq;
;     t += shx(t, 16, ln); t += shx(t, 32, ln);
;     return rsqrtf(t * (1.0f / 2048.0f) + RMS_EPS);
;     __device__ __forceinline__ void operator()(const f32x4 (&acc)[2][2][4][2], const Unit& u, int wr, int wc, int fr, int fq) const {
;     ...
;             for (int m = 0; m < 4; ++m) { const int row = row0 + ai * HALF + m * 16; const float rs = row_rstd(ssq, row, fr, fq), rs2 = rs * rs, nrl = -1.4426950408889634f * rs;
.LBB0_739:
	s_cmp_eq_u32 s26, s98
	s_cbranch_scc1 .Lsw1_have
	v_and_b32_e32 v153, 15, v167
	v_lshrrev_b32_e32 v154, 4, v167
	s_lshl_b32 s4, s26, 8
	s_add_i32 s4, s4, s78
	v_or_b32_e32 v155, s4, v153
	v_lshlrev_b32_e32 v156, 7, v155
	v_lshl_add_u32 v156, v154, 5, v156
	v_add_u32_e32 v157, 0x1000, v156
	v_add_u32_e32 v158, 0x4000, v156
	v_add_u32_e32 v159, 0x5000, v156
	global_load_dwordx4 v[168:171], v156, s[12:13]
	global_load_dwordx4 v[172:175], v156, s[12:13] offset:16
	global_load_dwordx4 v[176:179], v156, s[12:13] offset:2048
	global_load_dwordx4 v[180:183], v156, s[12:13] offset:2064
	global_load_dwordx4 v[184:187], v157, s[12:13]
	global_load_dwordx4 v[188:191], v157, s[12:13] offset:16
	global_load_dwordx4 v[192:195], v157, s[12:13] offset:2048
	global_load_dwordx4 v[196:199], v157, s[12:13] offset:2064
	global_load_dwordx4 v[200:203], v158, s[12:13]
	global_load_dwordx4 v[204:207], v158, s[12:13] offset:16
	global_load_dwordx4 v[208:211], v158, s[12:13] offset:2048
	global_load_dwordx4 v[212:215], v158, s[12:13] offset:2064
	global_load_dwordx4 v[216:219], v159, s[12:13]
	global_load_dwordx4 v[220:223], v159, s[12:13] offset:16
	global_load_dwordx4 v[224:227], v159, s[12:13] offset:2048
	global_load_dwordx4 v[228:231], v159, s[12:13] offset:2064
	v_xor_b32_e32 v160, 16, v167
	v_xor_b32_e32 v161, 32, v167
	v_lshlrev_b32_e32 v160, 2, v160
	v_lshlrev_b32_e32 v161, 2, v161
	s_waitcnt vmcnt(0)
	v_add_f32_e32 v168, v168, v169
	v_add_f32_e32 v176, v176, v177
	v_add_f32_e32 v184, v184, v185
	v_add_f32_e32 v192, v192, v193
	v_add_f32_e32 v200, v200, v201
	v_add_f32_e32 v208, v208, v209
	v_add_f32_e32 v216, v216, v217
	v_add_f32_e32 v224, v224, v225
	v_add_f32_e32 v170, v170, v171
	v_add_f32_e32 v178, v178, v179
	v_add_f32_e32 v186, v186, v187
	v_add_f32_e32 v194, v194, v195
	v_add_f32_e32 v202, v202, v203
	v_add_f32_e32 v210, v210, v211
	v_add_f32_e32 v218, v218, v219
	v_add_f32_e32 v226, v226, v227
	v_add_f32_e32 v172, v172, v173
	v_add_f32_e32 v180, v180, v181
	v_add_f32_e32 v188, v188, v189
	v_add_f32_e32 v196, v196, v197
	v_add_f32_e32 v204, v204, v205
	v_add_f32_e32 v212, v212, v213
	v_add_f32_e32 v220, v220, v221
	v_add_f32_e32 v228, v228, v229
	v_add_f32_e32 v174, v174, v175
	v_add_f32_e32 v182, v182, v183
	v_add_f32_e32 v190, v190, v191
	v_add_f32_e32 v198, v198, v199
	v_add_f32_e32 v206, v206, v207
	v_add_f32_e32 v214, v214, v215
	v_add_f32_e32 v222, v222, v223
	v_add_f32_e32 v230, v230, v231
	v_add_f32_e32 v168, v168, v170
	v_add_f32_e32 v176, v176, v178
	v_add_f32_e32 v184, v184, v186
	v_add_f32_e32 v192, v192, v194
	v_add_f32_e32 v200, v200, v202
	v_add_f32_e32 v208, v208, v210
	v_add_f32_e32 v216, v216, v218
	v_add_f32_e32 v224, v224, v226
	v_add_f32_e32 v172, v172, v174
	v_add_f32_e32 v180, v180, v182
	v_add_f32_e32 v188, v188, v190
	v_add_f32_e32 v196, v196, v198
	v_add_f32_e32 v204, v204, v206
	v_add_f32_e32 v212, v212, v214
	v_add_f32_e32 v220, v220, v222
	v_add_f32_e32 v228, v228, v230
	v_add_f32_e32 v168, v168, v172
	v_add_f32_e32 v176, v176, v180
	v_add_f32_e32 v184, v184, v188
	v_add_f32_e32 v192, v192, v196
	v_add_f32_e32 v200, v200, v204
	v_add_f32_e32 v208, v208, v212
	v_add_f32_e32 v216, v216, v220
	v_add_f32_e32 v224, v224, v228
	ds_bpermute_b32 v242, v160, v168
	ds_bpermute_b32 v243, v160, v176
	ds_bpermute_b32 v244, v160, v184
	ds_bpermute_b32 v245, v160, v192
	ds_bpermute_b32 v246, v160, v200
	ds_bpermute_b32 v247, v160, v208
	ds_bpermute_b32 v248, v160, v216
	ds_bpermute_b32 v249, v160, v224
	s_waitcnt lgkmcnt(0)
	v_add_f32_e32 v168, v168, v242
	v_add_f32_e32 v176, v176, v243
	v_add_f32_e32 v184, v184, v244
	v_add_f32_e32 v192, v192, v245
	v_add_f32_e32 v200, v200, v246
	v_add_f32_e32 v208, v208, v247
	v_add_f32_e32 v216, v216, v248
	v_add_f32_e32 v224, v224, v249
	ds_bpermute_b32 v242, v161, v168
	ds_bpermute_b32 v243, v161, v176
	ds_bpermute_b32 v244, v161, v184
	ds_bpermute_b32 v245, v161, v192
	ds_bpermute_b32 v246, v161, v200
	ds_bpermute_b32 v247, v161, v208
	ds_bpermute_b32 v248, v161, v216
	ds_bpermute_b32 v249, v161, v224
	s_waitcnt lgkmcnt(0)
	v_add_f32_e32 v168, v168, v242
	v_add_f32_e32 v176, v176, v243
	v_add_f32_e32 v184, v184, v244
	v_add_f32_e32 v192, v192, v245
	v_add_f32_e32 v200, v200, v246
	v_add_f32_e32 v208, v208, v247
	v_add_f32_e32 v216, v216, v248
	v_add_f32_e32 v224, v224, v249
	v_fmamk_f32 v168, v168, 0x3a000000, v152
	v_fmamk_f32 v176, v176, 0x3a000000, v152
	v_fmamk_f32 v184, v184, 0x3a000000, v152
	v_fmamk_f32 v192, v192, 0x3a000000, v152
	v_fmamk_f32 v200, v200, 0x3a000000, v152
	v_fmamk_f32 v208, v208, 0x3a000000, v152
	v_fmamk_f32 v216, v216, 0x3a000000, v152
	v_fmamk_f32 v224, v224, 0x3a000000, v152
	v_rsq_f32_e32 v169, v168
	v_rsq_f32_e32 v177, v176
	v_rsq_f32_e32 v185, v184
	v_rsq_f32_e32 v193, v192
	v_rsq_f32_e32 v201, v200
	v_rsq_f32_e32 v209, v208
	v_rsq_f32_e32 v217, v216
	v_rsq_f32_e32 v225, v224
	v_mul_f32_e32 v226, 0xbfb8aa3b, v169
	v_mul_f32_e32 v227, 0xbfb8aa3b, v177
	v_mul_f32_e32 v228, 0xbfb8aa3b, v185
	v_mul_f32_e32 v229, 0xbfb8aa3b, v193
	v_mul_f32_e32 v230, 0xbfb8aa3b, v201
	v_mul_f32_e32 v231, 0xbfb8aa3b, v209
	v_mul_f32_e32 v232, 0xbfb8aa3b, v217
	v_mul_f32_e32 v233, 0xbfb8aa3b, v225
	v_mul_f32_e32 v234, v169, v169
	v_mul_f32_e32 v235, v177, v177
	v_mul_f32_e32 v236, v185, v185
	v_mul_f32_e32 v237, v193, v193
	v_mul_f32_e32 v238, v201, v201
	v_mul_f32_e32 v239, v209, v209
	v_mul_f32_e32 v240, v217, v217
	v_mul_f32_e32 v241, v225, v225
	s_mov_b32 s98, s26
; __device__ __forceinline__ unsigned cvt_pk_bf16(float lo, float hi) { unsigned r; asm volatile("v_cvt_pk_bf16_f32 %0, %1, %2" : "=v"(r) : "v"(lo), "v"(hi)); return r; }
;     __device__ __forceinline__ void operator()(const f32x4 (&acc)[2][2][4][2], const Unit& u, int wr, int wc, int fr, int fq) const {
;         const int row0 = u.pm * BM + wr * 64 + fr, ch0 = u.pn * 128 + wc * 32 + 8 * fq;
; #pragma unroll
;         for (int ai = 0; ai < 2; ++ai)
; #pragma unroll
;             for (int m = 0; m < 4; ++m) { const int row = row0 + ai * HALF + m * 16; const float rs = row_rstd(ssq, row, fr, fq), rs2 = rs * rs, nrl = -1.4426950408889634f * rs;
;                 float o[8];
; #pragma unroll
;                 for (int n = 0; n < 2; ++n) { const f32x4 g = acc[ai][0][m][n], gu = g * acc[ai][1][m][n] * rs2;
; #pragma unroll
;                     for (int j = 0; j < 4; ++j) o[4 * n + j] = gu[j] * __builtin_amdgcn_rcpf(1.0f + __builtin_amdgcn_exp2f(g[j] * nrl)); }
;                 u32x4 w; w.x = cvt_pk_bf16(o[0], o[1]); w.y = cvt_pk_bf16(o[2], o[3]); w.z = cvt_pk_bf16(o[4], o[5]); w.w = cvt_pk_bf16(o[6], o[7]);
;                 *(u32x4*)(ACT + (size_t)row * 5632 + ch0) = w;
.Lsw1_have:
	v_and_b32_e32 v153, 15, v167
	v_lshrrev_b32_e32 v154, 4, v167
	s_lshl_b32 s4, s26, 8
	s_add_i32 s4, s4, s78
	v_or_b32_e32 v155, s4, v153
	s_lshl_b32 s4, s55, 7
	s_or_b32 s4, s4, s82
	v_lshl_add_u32 v162, v154, 3, s4
	v_lshlrev_b32_e32 v162, 1, v162
	v_mul_u32_u24_e32 v163, 0x2c00, v155
	v_add_u32_e32 v162, v162, v163
	v_mov_b32_e32 v164, v162
	v_mul_f32_e32 v124, v116, v124
	v_mul_f32_e32 v125, v117, v125
	v_mul_f32_e32 v126, v118, v126
	v_mul_f32_e32 v127, v119, v127
	v_mul_f32_e32 v120, v112, v120
	v_mul_f32_e32 v121, v113, v121
	v_mul_f32_e32 v122, v114, v122
	v_mul_f32_e32 v123, v115, v123
	v_mul_f32_e32 v116, v116, v226
	v_mul_f32_e32 v117, v117, v226
	v_mul_f32_e32 v118, v118, v226
	v_mul_f32_e32 v119, v119, v226
	v_mul_f32_e32 v112, v112, v226
	v_mul_f32_e32 v113, v113, v226
	v_mul_f32_e32 v114, v114, v226
	v_mul_f32_e32 v115, v115, v226
	v_exp_f32_e32 v116, v116
	v_exp_f32_e32 v117, v117
	v_exp_f32_e32 v118, v118
	v_exp_f32_e32 v119, v119
	v_exp_f32_e32 v112, v112
	v_exp_f32_e32 v113, v113
	v_exp_f32_e32 v114, v114
	v_exp_f32_e32 v115, v115
	v_add_f32_e32 v116, 1.0, v116
	v_add_f32_e32 v117, 1.0, v117
	v_add_f32_e32 v118, 1.0, v118
	v_add_f32_e32 v119, 1.0, v119
	v_add_f32_e32 v112, 1.0, v112
	v_add_f32_e32 v113, 1.0, v113
	v_add_f32_e32 v114, 1.0, v114
	v_add_f32_e32 v115, 1.0, v115
	v_rcp_f32_e32 v116, v116
	v_rcp_f32_e32 v117, v117
	v_rcp_f32_e32 v118, v118
	v_rcp_f32_e32 v119, v119
	v_rcp_f32_e32 v112, v112
	v_rcp_f32_e32 v113, v113
	v_rcp_f32_e32 v114, v114
	v_rcp_f32_e32 v115, v115
	v_mul_f32_e32 v124, v124, v234
	v_mul_f32_e32 v125, v125, v234
	v_mul_f32_e32 v126, v126, v234
	v_mul_f32_e32 v127, v127, v234
	v_mul_f32_e32 v120, v120, v234
	v_mul_f32_e32 v121, v121, v234
	v_mul_f32_e32 v122, v122, v234
	v_mul_f32_e32 v123, v123, v234
	v_mul_f32_e32 v124, v124, v116
	v_mul_f32_e32 v125, v125, v117
	v_mul_f32_e32 v126, v126, v118
	v_mul_f32_e32 v127, v127, v119
	v_mul_f32_e32 v120, v120, v112
	v_mul_f32_e32 v121, v121, v113
	v_mul_f32_e32 v122, v122, v114
	v_mul_f32_e32 v123, v123, v115
	v_cvt_pk_bf16_f32 v116, v124, v125
	v_cvt_pk_bf16_f32 v117, v126, v127
	v_cvt_pk_bf16_f32 v118, v120, v121
	v_cvt_pk_bf16_f32 v119, v122, v123
	global_store_dwordx4 v164, v[116:119], s[10:11]
	v_add_u32_e32 v165, 0x2c000, v162
	v_mul_f32_e32 v108, v100, v108
	v_mul_f32_e32 v109, v101, v109
	v_mul_f32_e32 v110, v102, v110
	v_mul_f32_e32 v111, v103, v111
	v_mul_f32_e32 v104, v96, v104
	v_mul_f32_e32 v105, v97, v105
	v_mul_f32_e32 v106, v98, v106
	v_mul_f32_e32 v107, v99, v107
	v_mul_f32_e32 v100, v100, v227
	v_mul_f32_e32 v101, v101, v227
	v_mul_f32_e32 v102, v102, v227
	v_mul_f32_e32 v103, v103, v227
	v_mul_f32_e32 v96, v96, v227
	v_mul_f32_e32 v97, v97, v227
	v_mul_f32_e32 v98, v98, v227
	v_mul_f32_e32 v99, v99, v227
	v_exp_f32_e32 v100, v100
	v_exp_f32_e32 v101, v101
	v_exp_f32_e32 v102, v102
	v_exp_f32_e32 v103, v103
	v_exp_f32_e32 v96, v96
	v_exp_f32_e32 v97, v97
	v_exp_f32_e32 v98, v98
	v_exp_f32_e32 v99, v99
	v_add_f32_e32 v100, 1.0, v100
	v_add_f32_e32 v101, 1.0, v101
	v_add_f32_e32 v102, 1.0, v102
	v_add_f32_e32 v103, 1.0, v103
	v_add_f32_e32 v96, 1.0, v96
	v_add_f32_e32 v97, 1.0, v97
	v_add_f32_e32 v98, 1.0, v98
	v_add_f32_e32 v99, 1.0, v99
	v_rcp_f32_e32 v100, v100
	v_rcp_f32_e32 v101, v101
	v_rcp_f32_e32 v102, v102
	v_rcp_f32_e32 v103, v103
	v_rcp_f32_e32 v96, v96
	v_rcp_f32_e32 v97, v97
	v_rcp_f32_e32 v98, v98
	v_rcp_f32_e32 v99, v99
	v_mul_f32_e32 v108, v108, v235
	v_mul_f32_e32 v109, v109, v235
	v_mul_f32_e32 v110, v110, v235
	v_mul_f32_e32 v111, v111, v235
	v_mul_f32_e32 v104, v104, v235
	v_mul_f32_e32 v105, v105, v235
	v_mul_f32_e32 v106, v106, v235
	v_mul_f32_e32 v107, v107, v235
	v_mul_f32_e32 v108, v108, v100
	v_mul_f32_e32 v109, v109, v101
	v_mul_f32_e32 v110, v110, v102
	v_mul_f32_e32 v111, v111, v103
	v_mul_f32_e32 v104, v104, v96
	v_mul_f32_e32 v105, v105, v97
	v_mul_f32_e32 v106, v106, v98
	v_mul_f32_e32 v107, v107, v99
	v_cvt_pk_bf16_f32 v100, v108, v109
	v_cvt_pk_bf16_f32 v101, v110, v111
	v_cvt_pk_bf16_f32 v102, v104, v105
	v_cvt_pk_bf16_f32 v103, v106, v107
	global_store_dwordx4 v165, v[100:103], s[10:11]
	v_add_u32_e32 v164, 0x58000, v162
	v_mul_f32_e32 v92, v84, v92
	v_mul_f32_e32 v93, v85, v93
	v_mul_f32_e32 v94, v86, v94
	v_mul_f32_e32 v95, v87, v95
	v_mul_f32_e32 v88, v80, v88
	v_mul_f32_e32 v89, v81, v89
	v_mul_f32_e32 v90, v82, v90
	v_mul_f32_e32 v91, v83, v91
	v_mul_f32_e32 v84, v84, v228
	v_mul_f32_e32 v85, v85, v228
	v_mul_f32_e32 v86, v86, v228
	v_mul_f32_e32 v87, v87, v228
	v_mul_f32_e32 v80, v80, v228
	v_mul_f32_e32 v81, v81, v228
	v_mul_f32_e32 v82, v82, v228
	v_mul_f32_e32 v83, v83, v228
	v_exp_f32_e32 v84, v84
	v_exp_f32_e32 v85, v85
	v_exp_f32_e32 v86, v86
	v_exp_f32_e32 v87, v87
	v_exp_f32_e32 v80, v80
	v_exp_f32_e32 v81, v81
	v_exp_f32_e32 v82, v82
	v_exp_f32_e32 v83, v83
	v_add_f32_e32 v84, 1.0, v84
	v_add_f32_e32 v85, 1.0, v85
	v_add_f32_e32 v86, 1.0, v86
	v_add_f32_e32 v87, 1.0, v87
	v_add_f32_e32 v80, 1.0, v80
	v_add_f32_e32 v81, 1.0, v81
	v_add_f32_e32 v82, 1.0, v82
	v_add_f32_e32 v83, 1.0, v83
	v_rcp_f32_e32 v84, v84
	v_rcp_f32_e32 v85, v85
	v_rcp_f32_e32 v86, v86
	v_rcp_f32_e32 v87, v87
	v_rcp_f32_e32 v80, v80
	v_rcp_f32_e32 v81, v81
	v_rcp_f32_e32 v82, v82
	v_rcp_f32_e32 v83, v83
	v_mul_f32_e32 v92, v92, v236
	v_mul_f32_e32 v93, v93, v236
	v_mul_f32_e32 v94, v94, v236
	v_mul_f32_e32 v95, v95, v236
	v_mul_f32_e32 v88, v88, v236
	v_mul_f32_e32 v89, v89, v236
	v_mul_f32_e32 v90, v90, v236
	v_mul_f32_e32 v91, v91, v236
	v_mul_f32_e32 v92, v92, v84
	v_mul_f32_e32 v93, v93, v85
	v_mul_f32_e32 v94, v94, v86
	v_mul_f32_e32 v95, v95, v87
	v_mul_f32_e32 v88, v88, v80
	v_mul_f32_e32 v89, v89, v81
; __device__ __forceinline__ unsigned cvt_pk_bf16(float lo, float hi) { unsigned r; asm volatile("v_cvt_pk_bf16_f32 %0, %1, %2" : "=v"(r) : "v"(lo), "v"(hi)); return r; }
;     __device__ __forceinline__ void operator()(const f32x4 (&acc)[2][2][4][2], const Unit& u, int wr, int wc, int fr, int fq) const {
;     ...
;             for (int m = 0; m < 4; ++m) { const int row = row0 + ai * HALF + m * 16; const float rs = row_rstd(ssq, row, fr, fq), rs2 = rs * rs, nrl = -1.4426950408889634f * rs;
;                 float o[8];
; #pragma unroll
;                 for (int n = 0; n < 2; ++n) { const f32x4 g = acc[ai][0][m][n], gu = g * acc[ai][1][m][n] * rs2;
; #pragma unroll
;                     for (int j = 0; j < 4; ++j) o[4 * n + j] = gu[j] * __builtin_amdgcn_rcpf(1.0f + __builtin_amdgcn_exp2f(g[j] * nrl)); }
;                 u32x4 w; w.x = cvt_pk_bf16(o[0], o[1]); w.y = cvt_pk_bf16(o[2], o[3]); w.z = cvt_pk_bf16(o[4], o[5]); w.w = cvt_pk_bf16(o[6], o[7]);
;                 *(u32x4*)(ACT + (size_t)row * 5632 + ch0) = w;
;                 asm volatile("" ::: "memory"); }
	v_mul_f32_e32 v90, v90, v82
	v_mul_f32_e32 v91, v91, v83
	v_cvt_pk_bf16_f32 v84, v92, v93
	v_cvt_pk_bf16_f32 v85, v94, v95
	v_cvt_pk_bf16_f32 v86, v88, v89
	v_cvt_pk_bf16_f32 v87, v90, v91
	global_store_dwordx4 v164, v[84:87], s[10:11]
	v_add_u32_e32 v165, 0x84000, v162
	v_mul_f32_e32 v76, v68, v76
	v_mul_f32_e32 v77, v69, v77
	v_mul_f32_e32 v78, v70, v78
	v_mul_f32_e32 v79, v71, v79
	v_mul_f32_e32 v72, v64, v72
	v_mul_f32_e32 v73, v65, v73
	v_mul_f32_e32 v74, v66, v74
	v_mul_f32_e32 v75, v67, v75
	v_mul_f32_e32 v68, v68, v229
	v_mul_f32_e32 v69, v69, v229
	v_mul_f32_e32 v70, v70, v229
	v_mul_f32_e32 v71, v71, v229
	v_mul_f32_e32 v64, v64, v229
	v_mul_f32_e32 v65, v65, v229
	v_mul_f32_e32 v66, v66, v229
	v_mul_f32_e32 v67, v67, v229
	v_exp_f32_e32 v68, v68
	v_exp_f32_e32 v69, v69
	v_exp_f32_e32 v70, v70
	v_exp_f32_e32 v71, v71
	v_exp_f32_e32 v64, v64
	v_exp_f32_e32 v65, v65
	v_exp_f32_e32 v66, v66
	v_exp_f32_e32 v67, v67
	v_add_f32_e32 v68, 1.0, v68
	v_add_f32_e32 v69, 1.0, v69
	v_add_f32_e32 v70, 1.0, v70
	v_add_f32_e32 v71, 1.0, v71
	v_add_f32_e32 v64, 1.0, v64
	v_add_f32_e32 v65, 1.0, v65
	v_add_f32_e32 v66, 1.0, v66
	v_add_f32_e32 v67, 1.0, v67
	v_rcp_f32_e32 v68, v68
	v_rcp_f32_e32 v69, v69
	v_rcp_f32_e32 v70, v70
	v_rcp_f32_e32 v71, v71
	v_rcp_f32_e32 v64, v64
	v_rcp_f32_e32 v65, v65
	v_rcp_f32_e32 v66, v66
	v_rcp_f32_e32 v67, v67
	v_mul_f32_e32 v76, v76, v237
	v_mul_f32_e32 v77, v77, v237
	v_mul_f32_e32 v78, v78, v237
	v_mul_f32_e32 v79, v79, v237
	v_mul_f32_e32 v72, v72, v237
	v_mul_f32_e32 v73, v73, v237
	v_mul_f32_e32 v74, v74, v237
	v_mul_f32_e32 v75, v75, v237
	v_mul_f32_e32 v76, v76, v68
	v_mul_f32_e32 v77, v77, v69
	v_mul_f32_e32 v78, v78, v70
	v_mul_f32_e32 v79, v79, v71
	v_mul_f32_e32 v72, v72, v64
	v_mul_f32_e32 v73, v73, v65
	v_mul_f32_e32 v74, v74, v66
	v_mul_f32_e32 v75, v75, v67
	v_cvt_pk_bf16_f32 v68, v76, v77
	v_cvt_pk_bf16_f32 v69, v78, v79
	v_cvt_pk_bf16_f32 v70, v72, v73
	v_cvt_pk_bf16_f32 v71, v74, v75
	global_store_dwordx4 v165, v[68:71], s[10:11]
	v_add_u32_e32 v164, 0x160000, v162
	v_mul_f32_e32 v60, v52, v60
	v_mul_f32_e32 v61, v53, v61
	v_mul_f32_e32 v62, v54, v62
	v_mul_f32_e32 v63, v55, v63
	v_mul_f32_e32 v56, v48, v56
	v_mul_f32_e32 v57, v49, v57
	v_mul_f32_e32 v58, v50, v58
	v_mul_f32_e32 v59, v51, v59
	v_mul_f32_e32 v52, v52, v230
	v_mul_f32_e32 v53, v53, v230
	v_mul_f32_e32 v54, v54, v230
	v_mul_f32_e32 v55, v55, v230
	v_mul_f32_e32 v48, v48, v230
	v_mul_f32_e32 v49, v49, v230
	v_mul_f32_e32 v50, v50, v230
	v_mul_f32_e32 v51, v51, v230
	v_exp_f32_e32 v52, v52
	v_exp_f32_e32 v53, v53
	v_exp_f32_e32 v54, v54
	v_exp_f32_e32 v55, v55
	v_exp_f32_e32 v48, v48
	v_exp_f32_e32 v49, v49
	v_exp_f32_e32 v50, v50
	v_exp_f32_e32 v51, v51
	v_add_f32_e32 v52, 1.0, v52
	v_add_f32_e32 v53, 1.0, v53
	v_add_f32_e32 v54, 1.0, v54
	v_add_f32_e32 v55, 1.0, v55
	v_add_f32_e32 v48, 1.0, v48
	v_add_f32_e32 v49, 1.0, v49
	v_add_f32_e32 v50, 1.0, v50
	v_add_f32_e32 v51, 1.0, v51
	v_rcp_f32_e32 v52, v52
	v_rcp_f32_e32 v53, v53
	v_rcp_f32_e32 v54, v54
	v_rcp_f32_e32 v55, v55
	v_rcp_f32_e32 v48, v48
	v_rcp_f32_e32 v49, v49
	v_rcp_f32_e32 v50, v50
	v_rcp_f32_e32 v51, v51
	v_mul_f32_e32 v60, v60, v238
	v_mul_f32_e32 v61, v61, v238
	v_mul_f32_e32 v62, v62, v238
	v_mul_f32_e32 v63, v63, v238
	v_mul_f32_e32 v56, v56, v238
	v_mul_f32_e32 v57, v57, v238
	v_mul_f32_e32 v58, v58, v238
	v_mul_f32_e32 v59, v59, v238
	v_mul_f32_e32 v60, v60, v52
	v_mul_f32_e32 v61, v61, v53
	v_mul_f32_e32 v62, v62, v54
	v_mul_f32_e32 v63, v63, v55
	v_mul_f32_e32 v56, v56, v48
	v_mul_f32_e32 v57, v57, v49
	v_mul_f32_e32 v58, v58, v50
	v_mul_f32_e32 v59, v59, v51
	v_cvt_pk_bf16_f32 v52, v60, v61
	v_cvt_pk_bf16_f32 v53, v62, v63
	v_cvt_pk_bf16_f32 v54, v56, v57
	v_cvt_pk_bf16_f32 v55, v58, v59
	global_store_dwordx4 v164, v[52:55], s[10:11]
	v_add_u32_e32 v165, 0x18c000, v162
	v_mul_f32_e32 v44, v36, v44
	v_mul_f32_e32 v45, v37, v45
	v_mul_f32_e32 v46, v38, v46
	v_mul_f32_e32 v47, v39, v47
	v_mul_f32_e32 v40, v32, v40
	v_mul_f32_e32 v41, v33, v41
	v_mul_f32_e32 v42, v34, v42
	v_mul_f32_e32 v43, v35, v43
	v_mul_f32_e32 v36, v36, v231
	v_mul_f32_e32 v37, v37, v231
	v_mul_f32_e32 v38, v38, v231
	v_mul_f32_e32 v39, v39, v231
	v_mul_f32_e32 v32, v32, v231
	v_mul_f32_e32 v33, v33, v231
	v_mul_f32_e32 v34, v34, v231
	v_mul_f32_e32 v35, v35, v231
	v_exp_f32_e32 v36, v36
	v_exp_f32_e32 v37, v37
	v_exp_f32_e32 v38, v38
	v_exp_f32_e32 v39, v39
	v_exp_f32_e32 v32, v32
	v_exp_f32_e32 v33, v33
	v_exp_f32_e32 v34, v34
	v_exp_f32_e32 v35, v35
	v_add_f32_e32 v36, 1.0, v36
	v_add_f32_e32 v37, 1.0, v37
	v_add_f32_e32 v38, 1.0, v38
	v_add_f32_e32 v39, 1.0, v39
; __device__ __forceinline__ unsigned cvt_pk_bf16(float lo, float hi) { unsigned r; asm volatile("v_cvt_pk_bf16_f32 %0, %1, %2" : "=v"(r) : "v"(lo), "v"(hi)); return r; }
;     __device__ __forceinline__ void operator()(const f32x4 (&acc)[2][2][4][2], const Unit& u, int wr, int wc, int fr, int fq) const {
;     ...
;             for (int m = 0; m < 4; ++m) { const int row = row0 + ai * HALF + m * 16; const float rs = row_rstd(ssq, row, fr, fq), rs2 = rs * rs, nrl = -1.4426950408889634f * rs;
;                 float o[8];
; #pragma unroll
;                 for (int n = 0; n < 2; ++n) { const f32x4 g = acc[ai][0][m][n], gu = g * acc[ai][1][m][n] * rs2;
; #pragma unroll
;                     for (int j = 0; j < 4; ++j) o[4 * n + j] = gu[j] * __builtin_amdgcn_rcpf(1.0f + __builtin_amdgcn_exp2f(g[j] * nrl)); }
;                 u32x4 w; w.x = cvt_pk_bf16(o[0], o[1]); w.y = cvt_pk_bf16(o[2], o[3]); w.z = cvt_pk_bf16(o[4], o[5]); w.w = cvt_pk_bf16(o[6], o[7]);
;                 *(u32x4*)(ACT + (size_t)row * 5632 + ch0) = w;
;                 asm volatile("" ::: "memory"); }
	v_add_f32_e32 v32, 1.0, v32
	v_add_f32_e32 v33, 1.0, v33
	v_add_f32_e32 v34, 1.0, v34
	v_add_f32_e32 v35, 1.0, v35
	v_rcp_f32_e32 v36, v36
	v_rcp_f32_e32 v37, v37
	v_rcp_f32_e32 v38, v38
	v_rcp_f32_e32 v39, v39
	v_rcp_f32_e32 v32, v32
	v_rcp_f32_e32 v33, v33
	v_rcp_f32_e32 v34, v34
	v_rcp_f32_e32 v35, v35
	v_mul_f32_e32 v44, v44, v239
	v_mul_f32_e32 v45, v45, v239
	v_mul_f32_e32 v46, v46, v239
	v_mul_f32_e32 v47, v47, v239
	v_mul_f32_e32 v40, v40, v239
	v_mul_f32_e32 v41, v41, v239
	v_mul_f32_e32 v42, v42, v239
	v_mul_f32_e32 v43, v43, v239
	v_mul_f32_e32 v44, v44, v36
	v_mul_f32_e32 v45, v45, v37
	v_mul_f32_e32 v46, v46, v38
	v_mul_f32_e32 v47, v47, v39
	v_mul_f32_e32 v40, v40, v32
	v_mul_f32_e32 v41, v41, v33
	v_mul_f32_e32 v42, v42, v34
	v_mul_f32_e32 v43, v43, v35
	v_cvt_pk_bf16_f32 v36, v44, v45
	v_cvt_pk_bf16_f32 v37, v46, v47
	v_cvt_pk_bf16_f32 v38, v40, v41
	v_cvt_pk_bf16_f32 v39, v42, v43
	global_store_dwordx4 v165, v[36:39], s[10:11]
	v_add_u32_e32 v164, 0x1b8000, v162
	v_mul_f32_e32 v28, v20, v28
	v_mul_f32_e32 v29, v21, v29
	v_mul_f32_e32 v30, v22, v30
	v_mul_f32_e32 v31, v23, v31
	v_mul_f32_e32 v24, v16, v24
	v_mul_f32_e32 v25, v17, v25
	v_mul_f32_e32 v26, v18, v26
	v_mul_f32_e32 v27, v19, v27
	v_mul_f32_e32 v20, v20, v232
	v_mul_f32_e32 v21, v21, v232
	v_mul_f32_e32 v22, v22, v232
	v_mul_f32_e32 v23, v23, v232
	v_mul_f32_e32 v16, v16, v232
	v_mul_f32_e32 v17, v17, v232
	v_mul_f32_e32 v18, v18, v232
	v_mul_f32_e32 v19, v19, v232
	v_exp_f32_e32 v20, v20
	v_exp_f32_e32 v21, v21
	v_exp_f32_e32 v22, v22
	v_exp_f32_e32 v23, v23
	v_exp_f32_e32 v16, v16
	v_exp_f32_e32 v17, v17
	v_exp_f32_e32 v18, v18
	v_exp_f32_e32 v19, v19
	v_add_f32_e32 v20, 1.0, v20
	v_add_f32_e32 v21, 1.0, v21
	v_add_f32_e32 v22, 1.0, v22
	v_add_f32_e32 v23, 1.0, v23
	v_add_f32_e32 v16, 1.0, v16
	v_add_f32_e32 v17, 1.0, v17
	v_add_f32_e32 v18, 1.0, v18
	v_add_f32_e32 v19, 1.0, v19
	v_rcp_f32_e32 v20, v20
	v_rcp_f32_e32 v21, v21
	v_rcp_f32_e32 v22, v22
	v_rcp_f32_e32 v23, v23
	v_rcp_f32_e32 v16, v16
	v_rcp_f32_e32 v17, v17
	v_rcp_f32_e32 v18, v18
	v_rcp_f32_e32 v19, v19
	v_mul_f32_e32 v28, v28, v240
	v_mul_f32_e32 v29, v29, v240
	v_mul_f32_e32 v30, v30, v240
	v_mul_f32_e32 v31, v31, v240
	v_mul_f32_e32 v24, v24, v240
	v_mul_f32_e32 v25, v25, v240
	v_mul_f32_e32 v26, v26, v240
	v_mul_f32_e32 v27, v27, v240
	v_mul_f32_e32 v28, v28, v20
	v_mul_f32_e32 v29, v29, v21
	v_mul_f32_e32 v30, v30, v22
	v_mul_f32_e32 v31, v31, v23
	v_mul_f32_e32 v24, v24, v16
	v_mul_f32_e32 v25, v25, v17
	v_mul_f32_e32 v26, v26, v18
	v_mul_f32_e32 v27, v27, v19
	v_cvt_pk_bf16_f32 v20, v28, v29
	v_cvt_pk_bf16_f32 v21, v30, v31
	v_cvt_pk_bf16_f32 v22, v24, v25
	v_cvt_pk_bf16_f32 v23, v26, v27
	global_store_dwordx4 v164, v[20:23], s[10:11]
	v_add_u32_e32 v165, 0x1e4000, v162
	v_mul_f32_e32 v12, v8, v12
	v_mul_f32_e32 v13, v9, v13
	v_mul_f32_e32 v14, v10, v14
	v_mul_f32_e32 v15, v11, v15
	v_mul_f32_e32 v0, v4, v0
	v_mul_f32_e32 v1, v5, v1
	v_mul_f32_e32 v2, v6, v2
	v_mul_f32_e32 v3, v7, v3
	v_mul_f32_e32 v8, v8, v233
	v_mul_f32_e32 v9, v9, v233
	v_mul_f32_e32 v10, v10, v233
	v_mul_f32_e32 v11, v11, v233
	v_mul_f32_e32 v4, v4, v233
	v_mul_f32_e32 v5, v5, v233
	v_mul_f32_e32 v6, v6, v233
	v_mul_f32_e32 v7, v7, v233
	v_exp_f32_e32 v8, v8
	v_exp_f32_e32 v9, v9
	v_exp_f32_e32 v10, v10
	v_exp_f32_e32 v11, v11
	v_exp_f32_e32 v4, v4
	v_exp_f32_e32 v5, v5
	v_exp_f32_e32 v6, v6
	v_exp_f32_e32 v7, v7
	v_add_f32_e32 v8, 1.0, v8
	v_add_f32_e32 v9, 1.0, v9
	v_add_f32_e32 v10, 1.0, v10
	v_add_f32_e32 v11, 1.0, v11
	v_add_f32_e32 v4, 1.0, v4
	v_add_f32_e32 v5, 1.0, v5
	v_add_f32_e32 v6, 1.0, v6
	v_add_f32_e32 v7, 1.0, v7
	v_rcp_f32_e32 v8, v8
	v_rcp_f32_e32 v9, v9
	v_rcp_f32_e32 v10, v10
	v_rcp_f32_e32 v11, v11
	v_rcp_f32_e32 v4, v4
	v_rcp_f32_e32 v5, v5
	v_rcp_f32_e32 v6, v6
	v_rcp_f32_e32 v7, v7
	v_mul_f32_e32 v12, v12, v241
	v_mul_f32_e32 v13, v13, v241
	v_mul_f32_e32 v14, v14, v241
	v_mul_f32_e32 v15, v15, v241
	v_mul_f32_e32 v0, v0, v241
	v_mul_f32_e32 v1, v1, v241
	v_mul_f32_e32 v2, v2, v241
	v_mul_f32_e32 v3, v3, v241
	v_mul_f32_e32 v12, v12, v8
	v_mul_f32_e32 v13, v13, v9
	v_mul_f32_e32 v14, v14, v10
	v_mul_f32_e32 v15, v15, v11
	v_mul_f32_e32 v0, v0, v4
	v_mul_f32_e32 v1, v1, v5
	v_mul_f32_e32 v2, v2, v6
	v_mul_f32_e32 v3, v3, v7
	v_cvt_pk_bf16_f32 v8, v12, v13
	v_cvt_pk_bf16_f32 v9, v14, v15
	v_cvt_pk_bf16_f32 v10, v0, v1
	v_cvt_pk_bf16_f32 v11, v2, v3
	global_store_dwordx4 v165, v[8:11], s[10:11]
	s_andn2_b64 vcc, exec, s[8:9]
	s_mov_b64 s[8:9], -1
	s_cbranch_vccnz .LBB0_732
	s_and_b64 vcc, exec, s[64:65]
	s_cbranch_vccnz .LBB0_731
	s_barrier
	s_branch .LBB0_731

; #define PG8_WAIT_V(n) asm volatile("s_waitcnt vmcnt(" #n ")" ::: "memory")
; #define PG8_BAR __builtin_amdgcn_s_barrier()
;     __host__ __device__ bool next(int i, Unit& u) const {
;         const long L = (long)i * G + c; if (L >= nwg) return false;
;         int wgid = (int)L; { const int q = nwg / NXCD, r = nwg % NXCD, xcd = wgid % NXCD, off = wgid / NXCD; wgid = (xcd < r ? xcd * (q + 1) : r * (q + 1) + (xcd - r) * q) + off; }
;         const int nig = WGM * nN, gid = wgid / nig, fm = gid * WGM, gsz = (nM - fm) < WGM ? (nM - fm) : WGM;
;         u.pm = fm + ((wgid % nig) % gsz); u.pn = (wgid % nig) / gsz; u.aoff = 0; return true;
; template <class Epi, class Sched, bool ALIGN_EPI = false, bool SP2 = false>
; __device__ __forceinline__ void gemm_phase(PG8_LAS unsigned char* lds, const Gemm g, const Sched& S, const Epi& E) {
;     ...
;     for (int i = 0; i < 2; ++i) { int R, C; stage_rc(tid * 16 + i * 8192, R, C); const int Rb = Epi::PERM ? ((R & ~31) + perm32(R & 31)) : R;
;         voffA[i] = (unsigned)(R * g.lda + C) * 2u; voffB[i] = (unsigned)(Rb * g.ldb + C) * 2u; }
;     constexpr unsigned kstep = (unsigned)(BK * 2);
;     const unsigned hstepA = (unsigned)HALF * g.lda * 2u, hstepB = (unsigned)HALF * g.ldb * 2u;
;     const unsigned tstepA = 2u * hstepA, tstepB = 2u * hstepB;
;     const unsigned ldsw = (unsigned)wid * 1024u;
;     const int aoff = lds_byte(wr * 64 + fr, fq * 8), boff = lds_byte(wc * 32 + fr, fq * 8);
;     ...
;     Unit cur, nxt; int ui = 0;
;     if (!S.next(0, cur)) return;
;     f32x4 acc[2][2][4][2];
; #pragma unroll
;     for (int a = 0; a < 2; ++a)
; #pragma unroll
;         for (int b = 0; b < 2; ++b)
; #pragma unroll
;             for (int m = 0; m < 4; ++m)
; #pragma unroll
;                 for (int n = 0; n < 2; ++n) acc[a][b][m][n] = (f32x4){0.f, 0.f, 0.f, 0.f};
;     bf16x8 At[4][2], B0[2][2], B1[2][2];
;     const char* cA = (const char*)g.A + (size_t)cur.pm * tstepA + cur.aoff; const char* cB = (const char*)g.Bt + (size_t)cur.pn * tstepB;
;     S.a_ready(cur);
;     if constexpr (SP2) {
;         PG8_STAGE(PG8_SB(0, 0), cB, voffB); PG8_STAGE(PG8_SB(0, 1), cB + hstepB, voffB); PG8_STAGE(PG8_SA(0, 0), cA, voffA); PG8_STAGE(PG8_SA(0, 1), cA + hstepA, voffA);
;         if (wr == 1) PG8_BAR;
;         PG8_WAIT_V(2); PG8_BAR;
.LBB0_1278:
	s_or_b64 exec, exec, s[54:55]
	s_mov_b64 s[8:9], s[62:63]
	v_mov_b32_e32 v8, v167
	s_and_b64 vcc, exec, s[52:53]
	s_waitcnt lgkmcnt(0)
	s_barrier
	s_mov_b32 s98, -1
	s_cbranch_vccz .LBB0_1294
	v_lshl_add_u32 v0, v8, 4, s47
	v_add_u32_e32 v1, 0x2000, v0
	v_ashrrev_i32_e32 v2, 31, v1
	v_lshrrev_b32_e32 v2, 22, v2
	v_add_u32_e32 v2, v1, v2
	v_ashrrev_i32_e32 v9, 10, v2
	v_mul_i32_i24_e32 v2, 0x400, v9
	v_sub_u32_e32 v1, v1, v2
	v_lshrrev_b32_e32 v2, 4, v1
	v_bitop3_b32 v1, v2, v1, 32 bitop3:0x6c
	v_ashrrev_i32_e32 v2, 31, v1
	v_lshrrev_b32_e32 v2, 26, v2
	v_add_u32_e32 v2, v1, v2
	v_ashrrev_i32_e32 v10, 6, v2
	v_lshlrev_b32_e32 v3, 3, v9
	v_and_b32_e32 v2, 0xffc0, v2
	v_and_b32_e32 v3, -16, v3
	v_sub_u32_e32 v1, v1, v2
	v_add_u32_e32 v3, v10, v3
	v_lshrrev_b16_e32 v2, 7, v1
	v_and_b32_e32 v4, 3, v10
	s_mov_b32 s4, 0xfffe0
	v_lshrrev_b32_e32 v5, 2, v3
	v_lshlrev_b32_e32 v6, 1, v3
	v_and_b32_e32 v2, 1, v2
	v_and_or_b32 v4, v3, s4, v4
	v_and_b32_e32 v5, 4, v5
	v_and_b32_e32 v6, 24, v6
	v_add_u16_e32 v1, v1, v2
	v_mov_b32_e32 v2, 1
	v_or3_b32 v4, v4, v5, v6
	v_lshlrev_b32_e32 v5, 5, v9
	v_ashrrev_i16_sdwa v1, v2, sext(v1) dst_sel:DWORD dst_unused:UNUSED_PAD src0_sel:DWORD src1_sel:BYTE_0
	v_and_b32_e32 v5, 32, v5
	v_bfe_i32 v11, v1, 0, 16
	v_add_lshl_u32 v1, v5, v11, 1
	v_lshl_add_u32 v128, v4, 12, v1
	v_lshl_add_u32 v130, v3, 12, v1
	v_ashrrev_i32_e32 v1, 31, v0
	v_lshrrev_b32_e32 v1, 22, v1
	v_add_u32_e32 v1, v0, v1
	v_ashrrev_i32_e32 v12, 10, v1
	v_mul_i32_i24_e32 v1, 0x400, v12
	s_load_dwordx2 s[8:9], s[8:9], 0x90
	v_sub_u32_e32 v0, v0, v1
	v_lshrrev_b32_e32 v1, 4, v0
	v_bitop3_b32 v0, v1, v0, 32 bitop3:0x6c
	v_ashrrev_i32_e32 v1, 31, v0
	v_lshrrev_b32_e32 v1, 26, v1
	s_waitcnt lgkmcnt(0)
	s_add_u32 s0, s8, 0xc800000
	v_add_u32_e32 v1, v0, v1
	v_lshlrev_b32_e32 v3, 3, v12
	s_addc_u32 s1, s9, 0
	v_ashrrev_i32_e32 v13, 6, v1
	v_and_b32_e32 v3, -16, v3
	s_add_u32 s3, s8, 0x5400000
	v_add_u32_e32 v3, v13, v3
	v_and_b32_e32 v4, 3, v13
	s_addc_u32 s24, s9, 0
	v_and_or_b32 v4, v3, s4, v4
	s_lshr_b32 s4, s80, 29
	s_add_i32 s4, s2, s4
	s_ashr_i32 s5, s4, 3
	s_and_b32 s4, s4, -8
	s_sub_i32 s4, s2, s4
	s_cmp_lt_i32 s4, 0
	s_movk_i32 s25, 0x161
	s_cselect_b32 s10, s25, 0x160
	s_mul_i32 s4, s4, s10
	s_add_i32 s4, s4, s5
	s_mul_hi_i32 s5, s4, 0x2e8ba2e9
	s_lshr_b32 s10, s5, 31
	s_ashr_i32 s5, s5, 6
	s_add_i32 s5, s5, s10
	s_lshl_b32 s10, s5, 3
	s_mulk_i32 s5, 0x160
	s_sub_i32 s4, s4, s5
	s_bfe_u32 s5, s4, 0x3001c
	s_add_i32 s5, s4, s5
	s_sext_i32_i16 s11, s5
	s_and_b32 s5, s5, 0xfff8
	s_sub_i32 s4, s4, s5
	s_sext_i32_i16 s4, s4
	v_lshrrev_b32_e32 v5, 2, v3
	v_lshlrev_b32_e32 v6, 1, v3
	v_and_b32_e32 v1, 0xc0, v1
	s_lshr_b32 s16, s11, 3
	s_add_i32 s26, s10, s4
	v_and_b32_e32 v5, 4, v5
	v_and_b32_e32 v6, 24, v6
	v_sub_u32_e32 v0, v0, v1
	s_ashr_i32 s27, s26, 31
	s_bfe_i64 s[10:11], s[16:17], 0x100000
	v_or3_b32 v4, v4, v5, v6
	v_lshlrev_b32_e32 v5, 5, v12
	v_ashrrev_i16_sdwa v0, v2, sext(v0) dst_sel:DWORD dst_unused:UNUSED_PAD src0_sel:DWORD src1_sel:BYTE_0
	s_lshl_b64 s[4:5], s[26:27], 20
	s_lshl_b64 s[10:11], s[10:11], 20
	v_and_b32_e32 v5, 32, v5
	v_bfe_i32 v14, v0, 0, 16
	s_add_u32 s30, s3, s10
	v_add_lshl_u32 v0, v5, v14, 1
	s_addc_u32 s31, s24, s11
	s_add_i32 s27, s47, 0
	v_lshl_add_u32 v132, v4, 12, v0
	s_add_i32 m0, s27, 0x10000
	v_lshl_add_u32 v134, v3, 12, v0
	global_load_lds_dwordx4 v132, s[30:31]
	s_add_i32 m0, s27, 0x12000
	s_add_u32 s10, s30, 0x80000
	global_load_lds_dwordx4 v128, s[30:31]
	s_addc_u32 s11, s31, 0
	s_add_i32 m0, s27, 0x14000
	v_mov_b32_e32 v133, 0
	global_load_lds_dwordx4 v132, s[10:11]
	s_add_i32 m0, s27, 0x16000
	s_add_u32 s28, s0, s4
	s_addc_u32 s29, s1, s5
	s_add_i32 s33, s27, 0x2000
	global_load_lds_dwordx4 v128, s[10:11]
	s_mov_b32 m0, s27
	s_add_u32 s4, s28, 0x80000
	global_load_lds_dwordx4 v134, s[28:29]
	s_mov_b32 m0, s33
	s_addc_u32 s5, s29, 0
	s_add_i32 s36, s27, 0x4000
	global_load_lds_dwordx4 v130, s[28:29]
	s_mov_b32 m0, s36
	s_add_i32 s37, s27, 0x6000
	global_load_lds_dwordx4 v134, s[4:5]
	s_mov_b32 m0, s37
	v_mov_b32_e32 v129, v133
	global_load_lds_dwordx4 v130, s[4:5]
	v_mov_b32_e32 v135, v133
	v_mov_b32_e32 v131, v133
	s_mov_b32 s38, 0
	v_lshl_add_u64 v[6:7], s[30:31], 0, v[132:133]
	v_lshl_add_u64 v[4:5], s[30:31], 0, v[128:129]
	v_lshl_add_u64 v[2:3], s[28:29], 0, v[134:135]
	s_and_b64 vcc, exec, s[66:67]
	v_lshl_add_u64 v[0:1], s[28:29], 0, v[130:131]
	s_cbranch_vccnz .LBB0_1281
	s_barrier

; __device__ __forceinline__ unsigned cvt_pk_bf16(float lo, float hi) { unsigned r; asm volatile("v_cvt_pk_bf16_f32 %0, %1, %2" : "=v"(r) : "v"(lo), "v"(hi)); return r; }
;     __device__ __forceinline__ void operator()(const f32x4 (&acc)[2][2][4][2], const Unit& u, int wr, int wc, int fr, int fq) const {
;         const int row0 = u.pm * BM + wr * 64 + fr, ch0 = u.pn * 128 + wc * 32 + 8 * fq;
; #pragma unroll
;         for (int ai = 0; ai < 2; ++ai)
; #pragma unroll
;             for (int m = 0; m < 4; ++m) { const int row = row0 + ai * HALF + m * 16; const float rs = row_rstd(ssq, row, fr, fq), rs2 = rs * rs, nrl = -1.4426950408889634f * rs;
;                 float o[8];
; #pragma unroll
;                 for (int n = 0; n < 2; ++n) { const f32x4 g = acc[ai][0][m][n], gu = g * acc[ai][1][m][n] * rs2;
; #pragma unroll
;                     for (int j = 0; j < 4; ++j) o[4 * n + j] = gu[j] * __builtin_amdgcn_rcpf(1.0f + __builtin_amdgcn_exp2f(g[j] * nrl)); }
;                 u32x4 w; w.x = cvt_pk_bf16(o[0], o[1]); w.y = cvt_pk_bf16(o[2], o[3]); w.z = cvt_pk_bf16(o[4], o[5]); w.w = cvt_pk_bf16(o[6], o[7]);
;                 *(u32x4*)(ACT + (size_t)row * 5632 + ch0) = w;
.Lsw2_have:
	v_and_b32_e32 v153, 15, v167
	v_lshrrev_b32_e32 v154, 4, v167
	s_lshl_b32 s4, s26, 8
	s_add_i32 s4, s4, s78
	v_or_b32_e32 v155, s4, v153
	s_lshl_b32 s4, s53, 7
	s_or_b32 s4, s4, s82
	v_lshl_add_u32 v162, v154, 3, s4
	v_lshlrev_b32_e32 v162, 1, v162
	v_mul_u32_u24_e32 v163, 0x2c00, v155
	v_add_u32_e32 v162, v162, v163
	v_mov_b32_e32 v164, v162
	v_mul_f32_e32 v124, v116, v124
	v_mul_f32_e32 v125, v117, v125
	v_mul_f32_e32 v126, v118, v126
	v_mul_f32_e32 v127, v119, v127
	v_mul_f32_e32 v120, v112, v120
	v_mul_f32_e32 v121, v113, v121
	v_mul_f32_e32 v122, v114, v122
	v_mul_f32_e32 v123, v115, v123
	v_mul_f32_e32 v116, v116, v226
	v_mul_f32_e32 v117, v117, v226
	v_mul_f32_e32 v118, v118, v226
	v_mul_f32_e32 v119, v119, v226
	v_mul_f32_e32 v112, v112, v226
	v_mul_f32_e32 v113, v113, v226
	v_mul_f32_e32 v114, v114, v226
	v_mul_f32_e32 v115, v115, v226
	v_exp_f32_e32 v116, v116
	v_exp_f32_e32 v117, v117
	v_exp_f32_e32 v118, v118
	v_exp_f32_e32 v119, v119
	v_exp_f32_e32 v112, v112
	v_exp_f32_e32 v113, v113
	v_exp_f32_e32 v114, v114
	v_exp_f32_e32 v115, v115
	v_add_f32_e32 v116, 1.0, v116
	v_add_f32_e32 v117, 1.0, v117
	v_add_f32_e32 v118, 1.0, v118
	v_add_f32_e32 v119, 1.0, v119
	v_add_f32_e32 v112, 1.0, v112
	v_add_f32_e32 v113, 1.0, v113
	v_add_f32_e32 v114, 1.0, v114
	v_add_f32_e32 v115, 1.0, v115
	v_rcp_f32_e32 v116, v116
	v_rcp_f32_e32 v117, v117
	v_rcp_f32_e32 v118, v118
	v_rcp_f32_e32 v119, v119
	v_rcp_f32_e32 v112, v112
	v_rcp_f32_e32 v113, v113
	v_rcp_f32_e32 v114, v114
	v_rcp_f32_e32 v115, v115
	v_mul_f32_e32 v124, v124, v234
	v_mul_f32_e32 v125, v125, v234
	v_mul_f32_e32 v126, v126, v234
	v_mul_f32_e32 v127, v127, v234
	v_mul_f32_e32 v120, v120, v234
	v_mul_f32_e32 v121, v121, v234
	v_mul_f32_e32 v122, v122, v234
	v_mul_f32_e32 v123, v123, v234
	v_mul_f32_e32 v124, v124, v116
	v_mul_f32_e32 v125, v125, v117
	v_mul_f32_e32 v126, v126, v118
	v_mul_f32_e32 v127, v127, v119
	v_mul_f32_e32 v120, v120, v112
	v_mul_f32_e32 v121, v121, v113
	v_mul_f32_e32 v122, v122, v114
	v_mul_f32_e32 v123, v123, v115
	v_cvt_pk_bf16_f32 v116, v124, v125
	v_cvt_pk_bf16_f32 v117, v126, v127
	v_cvt_pk_bf16_f32 v118, v120, v121
	v_cvt_pk_bf16_f32 v119, v122, v123
	global_store_dwordx4 v164, v[116:119], s[10:11]
	v_add_u32_e32 v165, 0x2c000, v162
	v_mul_f32_e32 v108, v100, v108
	v_mul_f32_e32 v109, v101, v109
	v_mul_f32_e32 v110, v102, v110
	v_mul_f32_e32 v111, v103, v111
	v_mul_f32_e32 v104, v96, v104
	v_mul_f32_e32 v105, v97, v105
	v_mul_f32_e32 v106, v98, v106
	v_mul_f32_e32 v107, v99, v107
	v_mul_f32_e32 v100, v100, v227
	v_mul_f32_e32 v101, v101, v227
	v_mul_f32_e32 v102, v102, v227
	v_mul_f32_e32 v103, v103, v227
	v_mul_f32_e32 v96, v96, v227
	v_mul_f32_e32 v97, v97, v227
	v_mul_f32_e32 v98, v98, v227
	v_mul_f32_e32 v99, v99, v227
	v_exp_f32_e32 v100, v100
	v_exp_f32_e32 v101, v101
	v_exp_f32_e32 v102, v102
	v_exp_f32_e32 v103, v103
	v_exp_f32_e32 v96, v96
	v_exp_f32_e32 v97, v97
	v_exp_f32_e32 v98, v98
	v_exp_f32_e32 v99, v99
	v_add_f32_e32 v100, 1.0, v100
	v_add_f32_e32 v101, 1.0, v101
	v_add_f32_e32 v102, 1.0, v102
	v_add_f32_e32 v103, 1.0, v103
	v_add_f32_e32 v96, 1.0, v96
	v_add_f32_e32 v97, 1.0, v97
	v_add_f32_e32 v98, 1.0, v98
	v_add_f32_e32 v99, 1.0, v99
	v_rcp_f32_e32 v100, v100
	v_rcp_f32_e32 v101, v101
	v_rcp_f32_e32 v102, v102
	v_rcp_f32_e32 v103, v103
	v_rcp_f32_e32 v96, v96
	v_rcp_f32_e32 v97, v97
	v_rcp_f32_e32 v98, v98
	v_rcp_f32_e32 v99, v99
	v_mul_f32_e32 v108, v108, v235
	v_mul_f32_e32 v109, v109, v235
	v_mul_f32_e32 v110, v110, v235
	v_mul_f32_e32 v111, v111, v235
	v_mul_f32_e32 v104, v104, v235
	v_mul_f32_e32 v105, v105, v235
	v_mul_f32_e32 v106, v106, v235
	v_mul_f32_e32 v107, v107, v235
	v_mul_f32_e32 v108, v108, v100
	v_mul_f32_e32 v109, v109, v101
	v_mul_f32_e32 v110, v110, v102
	v_mul_f32_e32 v111, v111, v103
	v_mul_f32_e32 v104, v104, v96
	v_mul_f32_e32 v105, v105, v97
	v_mul_f32_e32 v106, v106, v98
	v_mul_f32_e32 v107, v107, v99
	v_cvt_pk_bf16_f32 v100, v108, v109
	v_cvt_pk_bf16_f32 v101, v110, v111
	v_cvt_pk_bf16_f32 v102, v104, v105
	v_cvt_pk_bf16_f32 v103, v106, v107
	global_store_dwordx4 v165, v[100:103], s[10:11]
	v_add_u32_e32 v164, 0x58000, v162
	v_mul_f32_e32 v92, v84, v92
	v_mul_f32_e32 v93, v85, v93
	v_mul_f32_e32 v94, v86, v94
	v_mul_f32_e32 v95, v87, v95
	v_mul_f32_e32 v88, v80, v88
	v_mul_f32_e32 v89, v81, v89
	v_mul_f32_e32 v90, v82, v90
	v_mul_f32_e32 v91, v83, v91
	v_mul_f32_e32 v84, v84, v228
	v_mul_f32_e32 v85, v85, v228
	v_mul_f32_e32 v86, v86, v228
	v_mul_f32_e32 v87, v87, v228
	v_mul_f32_e32 v80, v80, v228
	v_mul_f32_e32 v81, v81, v228
	v_mul_f32_e32 v82, v82, v228
	v_mul_f32_e32 v83, v83, v228
	v_exp_f32_e32 v84, v84
	v_exp_f32_e32 v85, v85
	v_exp_f32_e32 v86, v86
	v_exp_f32_e32 v87, v87
	v_exp_f32_e32 v80, v80
	v_exp_f32_e32 v81, v81
	v_exp_f32_e32 v82, v82
	v_exp_f32_e32 v83, v83
	v_add_f32_e32 v84, 1.0, v84
	v_add_f32_e32 v85, 1.0, v85
	v_add_f32_e32 v86, 1.0, v86
	v_add_f32_e32 v87, 1.0, v87
	v_add_f32_e32 v80, 1.0, v80
	v_add_f32_e32 v81, 1.0, v81
	v_add_f32_e32 v82, 1.0, v82
	v_add_f32_e32 v83, 1.0, v83
	v_rcp_f32_e32 v84, v84
	v_rcp_f32_e32 v85, v85
	v_rcp_f32_e32 v86, v86
	v_rcp_f32_e32 v87, v87
	v_rcp_f32_e32 v80, v80
	v_rcp_f32_e32 v81, v81
	v_rcp_f32_e32 v82, v82
	v_rcp_f32_e32 v83, v83
	v_mul_f32_e32 v92, v92, v236
	v_mul_f32_e32 v93, v93, v236
	v_mul_f32_e32 v94, v94, v236
	v_mul_f32_e32 v95, v95, v236
	v_mul_f32_e32 v88, v88, v236
	v_mul_f32_e32 v89, v89, v236
	v_mul_f32_e32 v90, v90, v236
	v_mul_f32_e32 v91, v91, v236
	v_mul_f32_e32 v92, v92, v84
	v_mul_f32_e32 v93, v93, v85
	v_mul_f32_e32 v94, v94, v86
	v_mul_f32_e32 v95, v95, v87
	v_mul_f32_e32 v88, v88, v80
	v_mul_f32_e32 v89, v89, v81
; __device__ __forceinline__ unsigned cvt_pk_bf16(float lo, float hi) { unsigned r; asm volatile("v_cvt_pk_bf16_f32 %0, %1, %2" : "=v"(r) : "v"(lo), "v"(hi)); return r; }
;     __device__ __forceinline__ void operator()(const f32x4 (&acc)[2][2][4][2], const Unit& u, int wr, int wc, int fr, int fq) const {
;     ...
;             for (int m = 0; m < 4; ++m) { const int row = row0 + ai * HALF + m * 16; const float rs = row_rstd(ssq, row, fr, fq), rs2 = rs * rs, nrl = -1.4426950408889634f * rs;
;                 float o[8];
; #pragma unroll
;                 for (int n = 0; n < 2; ++n) { const f32x4 g = acc[ai][0][m][n], gu = g * acc[ai][1][m][n] * rs2;
; #pragma unroll
;                     for (int j = 0; j < 4; ++j) o[4 * n + j] = gu[j] * __builtin_amdgcn_rcpf(1.0f + __builtin_amdgcn_exp2f(g[j] * nrl)); }
;                 u32x4 w; w.x = cvt_pk_bf16(o[0], o[1]); w.y = cvt_pk_bf16(o[2], o[3]); w.z = cvt_pk_bf16(o[4], o[5]); w.w = cvt_pk_bf16(o[6], o[7]);
;                 *(u32x4*)(ACT + (size_t)row * 5632 + ch0) = w;
;                 asm volatile("" ::: "memory"); }
	v_mul_f32_e32 v90, v90, v82
	v_mul_f32_e32 v91, v91, v83
	v_cvt_pk_bf16_f32 v84, v92, v93
	v_cvt_pk_bf16_f32 v85, v94, v95
	v_cvt_pk_bf16_f32 v86, v88, v89
	v_cvt_pk_bf16_f32 v87, v90, v91
	global_store_dwordx4 v164, v[84:87], s[10:11]
	v_add_u32_e32 v165, 0x84000, v162
	v_mul_f32_e32 v76, v68, v76
	v_mul_f32_e32 v77, v69, v77
	v_mul_f32_e32 v78, v70, v78
	v_mul_f32_e32 v79, v71, v79
	v_mul_f32_e32 v72, v64, v72
	v_mul_f32_e32 v73, v65, v73
	v_mul_f32_e32 v74, v66, v74
	v_mul_f32_e32 v75, v67, v75
	v_mul_f32_e32 v68, v68, v229
	v_mul_f32_e32 v69, v69, v229
	v_mul_f32_e32 v70, v70, v229
	v_mul_f32_e32 v71, v71, v229
	v_mul_f32_e32 v64, v64, v229
	v_mul_f32_e32 v65, v65, v229
	v_mul_f32_e32 v66, v66, v229
	v_mul_f32_e32 v67, v67, v229
	v_exp_f32_e32 v68, v68
	v_exp_f32_e32 v69, v69
	v_exp_f32_e32 v70, v70
	v_exp_f32_e32 v71, v71
	v_exp_f32_e32 v64, v64
	v_exp_f32_e32 v65, v65
	v_exp_f32_e32 v66, v66
	v_exp_f32_e32 v67, v67
	v_add_f32_e32 v68, 1.0, v68
	v_add_f32_e32 v69, 1.0, v69
	v_add_f32_e32 v70, 1.0, v70
	v_add_f32_e32 v71, 1.0, v71
	v_add_f32_e32 v64, 1.0, v64
	v_add_f32_e32 v65, 1.0, v65
	v_add_f32_e32 v66, 1.0, v66
	v_add_f32_e32 v67, 1.0, v67
	v_rcp_f32_e32 v68, v68
	v_rcp_f32_e32 v69, v69
	v_rcp_f32_e32 v70, v70
	v_rcp_f32_e32 v71, v71
	v_rcp_f32_e32 v64, v64
	v_rcp_f32_e32 v65, v65
	v_rcp_f32_e32 v66, v66
	v_rcp_f32_e32 v67, v67
	v_mul_f32_e32 v76, v76, v237
	v_mul_f32_e32 v77, v77, v237
	v_mul_f32_e32 v78, v78, v237
	v_mul_f32_e32 v79, v79, v237
	v_mul_f32_e32 v72, v72, v237
	v_mul_f32_e32 v73, v73, v237
	v_mul_f32_e32 v74, v74, v237
	v_mul_f32_e32 v75, v75, v237
	v_mul_f32_e32 v76, v76, v68
	v_mul_f32_e32 v77, v77, v69
	v_mul_f32_e32 v78, v78, v70
	v_mul_f32_e32 v79, v79, v71
	v_mul_f32_e32 v72, v72, v64
	v_mul_f32_e32 v73, v73, v65
	v_mul_f32_e32 v74, v74, v66
	v_mul_f32_e32 v75, v75, v67
	v_cvt_pk_bf16_f32 v68, v76, v77
	v_cvt_pk_bf16_f32 v69, v78, v79
	v_cvt_pk_bf16_f32 v70, v72, v73
	v_cvt_pk_bf16_f32 v71, v74, v75
	global_store_dwordx4 v165, v[68:71], s[10:11]
	v_add_u32_e32 v164, 0x160000, v162
	v_mul_f32_e32 v60, v52, v60
	v_mul_f32_e32 v61, v53, v61
	v_mul_f32_e32 v62, v54, v62
	v_mul_f32_e32 v63, v55, v63
	v_mul_f32_e32 v56, v48, v56
	v_mul_f32_e32 v57, v49, v57
	v_mul_f32_e32 v58, v50, v58
	v_mul_f32_e32 v59, v51, v59
	v_mul_f32_e32 v52, v52, v230
	v_mul_f32_e32 v53, v53, v230
	v_mul_f32_e32 v54, v54, v230
	v_mul_f32_e32 v55, v55, v230
	v_mul_f32_e32 v48, v48, v230
	v_mul_f32_e32 v49, v49, v230
	v_mul_f32_e32 v50, v50, v230
	v_mul_f32_e32 v51, v51, v230
	v_exp_f32_e32 v52, v52
	v_exp_f32_e32 v53, v53
	v_exp_f32_e32 v54, v54
	v_exp_f32_e32 v55, v55
	v_exp_f32_e32 v48, v48
	v_exp_f32_e32 v49, v49
	v_exp_f32_e32 v50, v50
	v_exp_f32_e32 v51, v51
	v_add_f32_e32 v52, 1.0, v52
	v_add_f32_e32 v53, 1.0, v53
	v_add_f32_e32 v54, 1.0, v54
	v_add_f32_e32 v55, 1.0, v55
	v_add_f32_e32 v48, 1.0, v48
	v_add_f32_e32 v49, 1.0, v49
	v_add_f32_e32 v50, 1.0, v50
	v_add_f32_e32 v51, 1.0, v51
	v_rcp_f32_e32 v52, v52
	v_rcp_f32_e32 v53, v53
	v_rcp_f32_e32 v54, v54
	v_rcp_f32_e32 v55, v55
	v_rcp_f32_e32 v48, v48
	v_rcp_f32_e32 v49, v49
	v_rcp_f32_e32 v50, v50
	v_rcp_f32_e32 v51, v51
	v_mul_f32_e32 v60, v60, v238
	v_mul_f32_e32 v61, v61, v238
	v_mul_f32_e32 v62, v62, v238
	v_mul_f32_e32 v63, v63, v238
	v_mul_f32_e32 v56, v56, v238
	v_mul_f32_e32 v57, v57, v238
	v_mul_f32_e32 v58, v58, v238
	v_mul_f32_e32 v59, v59, v238
	v_mul_f32_e32 v60, v60, v52
	v_mul_f32_e32 v61, v61, v53
	v_mul_f32_e32 v62, v62, v54
	v_mul_f32_e32 v63, v63, v55
	v_mul_f32_e32 v56, v56, v48
	v_mul_f32_e32 v57, v57, v49
	v_mul_f32_e32 v58, v58, v50
	v_mul_f32_e32 v59, v59, v51
	v_cvt_pk_bf16_f32 v52, v60, v61
	v_cvt_pk_bf16_f32 v53, v62, v63
	v_cvt_pk_bf16_f32 v54, v56, v57
	v_cvt_pk_bf16_f32 v55, v58, v59
	global_store_dwordx4 v164, v[52:55], s[10:11]
	v_add_u32_e32 v165, 0x18c000, v162
	v_mul_f32_e32 v44, v36, v44
	v_mul_f32_e32 v45, v37, v45
	v_mul_f32_e32 v46, v38, v46
	v_mul_f32_e32 v47, v39, v47
	v_mul_f32_e32 v40, v32, v40
	v_mul_f32_e32 v41, v33, v41
	v_mul_f32_e32 v42, v34, v42
	v_mul_f32_e32 v43, v35, v43
	v_mul_f32_e32 v36, v36, v231
	v_mul_f32_e32 v37, v37, v231
	v_mul_f32_e32 v38, v38, v231
	v_mul_f32_e32 v39, v39, v231
	v_mul_f32_e32 v32, v32, v231
	v_mul_f32_e32 v33, v33, v231
	v_mul_f32_e32 v34, v34, v231
	v_mul_f32_e32 v35, v35, v231
	v_exp_f32_e32 v36, v36
	v_exp_f32_e32 v37, v37
	v_exp_f32_e32 v38, v38
	v_exp_f32_e32 v39, v39
	v_exp_f32_e32 v32, v32
	v_exp_f32_e32 v33, v33
	v_exp_f32_e32 v34, v34
	v_exp_f32_e32 v35, v35
	v_add_f32_e32 v36, 1.0, v36
	v_add_f32_e32 v37, 1.0, v37
	v_add_f32_e32 v38, 1.0, v38
	v_add_f32_e32 v39, 1.0, v39
; __device__ __forceinline__ unsigned cvt_pk_bf16(float lo, float hi) { unsigned r; asm volatile("v_cvt_pk_bf16_f32 %0, %1, %2" : "=v"(r) : "v"(lo), "v"(hi)); return r; }
;     __device__ __forceinline__ void operator()(const f32x4 (&acc)[2][2][4][2], const Unit& u, int wr, int wc, int fr, int fq) const {
;     ...
;             for (int m = 0; m < 4; ++m) { const int row = row0 + ai * HALF + m * 16; const float rs = row_rstd(ssq, row, fr, fq), rs2 = rs * rs, nrl = -1.4426950408889634f * rs;
;                 float o[8];
; #pragma unroll
;                 for (int n = 0; n < 2; ++n) { const f32x4 g = acc[ai][0][m][n], gu = g * acc[ai][1][m][n] * rs2;
; #pragma unroll
;                     for (int j = 0; j < 4; ++j) o[4 * n + j] = gu[j] * __builtin_amdgcn_rcpf(1.0f + __builtin_amdgcn_exp2f(g[j] * nrl)); }
;                 u32x4 w; w.x = cvt_pk_bf16(o[0], o[1]); w.y = cvt_pk_bf16(o[2], o[3]); w.z = cvt_pk_bf16(o[4], o[5]); w.w = cvt_pk_bf16(o[6], o[7]);
;                 *(u32x4*)(ACT + (size_t)row * 5632 + ch0) = w;
;                 asm volatile("" ::: "memory"); }
	v_add_f32_e32 v32, 1.0, v32
	v_add_f32_e32 v33, 1.0, v33
	v_add_f32_e32 v34, 1.0, v34
	v_add_f32_e32 v35, 1.0, v35
	v_rcp_f32_e32 v36, v36
	v_rcp_f32_e32 v37, v37
	v_rcp_f32_e32 v38, v38
	v_rcp_f32_e32 v39, v39
	v_rcp_f32_e32 v32, v32
	v_rcp_f32_e32 v33, v33
	v_rcp_f32_e32 v34, v34
	v_rcp_f32_e32 v35, v35
	v_mul_f32_e32 v44, v44, v239
	v_mul_f32_e32 v45, v45, v239
	v_mul_f32_e32 v46, v46, v239
	v_mul_f32_e32 v47, v47, v239
	v_mul_f32_e32 v40, v40, v239
	v_mul_f32_e32 v41, v41, v239
	v_mul_f32_e32 v42, v42, v239
	v_mul_f32_e32 v43, v43, v239
	v_mul_f32_e32 v44, v44, v36
	v_mul_f32_e32 v45, v45, v37
	v_mul_f32_e32 v46, v46, v38
	v_mul_f32_e32 v47, v47, v39
	v_mul_f32_e32 v40, v40, v32
	v_mul_f32_e32 v41, v41, v33
	v_mul_f32_e32 v42, v42, v34
	v_mul_f32_e32 v43, v43, v35
	v_cvt_pk_bf16_f32 v36, v44, v45
	v_cvt_pk_bf16_f32 v37, v46, v47
	v_cvt_pk_bf16_f32 v38, v40, v41
	v_cvt_pk_bf16_f32 v39, v42, v43
	global_store_dwordx4 v165, v[36:39], s[10:11]
	v_add_u32_e32 v164, 0x1b8000, v162
	v_mul_f32_e32 v28, v20, v28
	v_mul_f32_e32 v29, v21, v29
	v_mul_f32_e32 v30, v22, v30
	v_mul_f32_e32 v31, v23, v31
	v_mul_f32_e32 v24, v16, v24
	v_mul_f32_e32 v25, v17, v25
	v_mul_f32_e32 v26, v18, v26
	v_mul_f32_e32 v27, v19, v27
	v_mul_f32_e32 v20, v20, v232
	v_mul_f32_e32 v21, v21, v232
	v_mul_f32_e32 v22, v22, v232
	v_mul_f32_e32 v23, v23, v232
	v_mul_f32_e32 v16, v16, v232
	v_mul_f32_e32 v17, v17, v232
	v_mul_f32_e32 v18, v18, v232
	v_mul_f32_e32 v19, v19, v232
	v_exp_f32_e32 v20, v20
	v_exp_f32_e32 v21, v21
	v_exp_f32_e32 v22, v22
	v_exp_f32_e32 v23, v23
	v_exp_f32_e32 v16, v16
	v_exp_f32_e32 v17, v17
	v_exp_f32_e32 v18, v18
	v_exp_f32_e32 v19, v19
	v_add_f32_e32 v20, 1.0, v20
	v_add_f32_e32 v21, 1.0, v21
	v_add_f32_e32 v22, 1.0, v22
	v_add_f32_e32 v23, 1.0, v23
	v_add_f32_e32 v16, 1.0, v16
	v_add_f32_e32 v17, 1.0, v17
	v_add_f32_e32 v18, 1.0, v18
	v_add_f32_e32 v19, 1.0, v19
	v_rcp_f32_e32 v20, v20
	v_rcp_f32_e32 v21, v21
	v_rcp_f32_e32 v22, v22
	v_rcp_f32_e32 v23, v23
	v_rcp_f32_e32 v16, v16
	v_rcp_f32_e32 v17, v17
	v_rcp_f32_e32 v18, v18
	v_rcp_f32_e32 v19, v19
	v_mul_f32_e32 v28, v28, v240
	v_mul_f32_e32 v29, v29, v240
	v_mul_f32_e32 v30, v30, v240
	v_mul_f32_e32 v31, v31, v240
	v_mul_f32_e32 v24, v24, v240
	v_mul_f32_e32 v25, v25, v240
	v_mul_f32_e32 v26, v26, v240
	v_mul_f32_e32 v27, v27, v240
	v_mul_f32_e32 v28, v28, v20
	v_mul_f32_e32 v29, v29, v21
	v_mul_f32_e32 v30, v30, v22
	v_mul_f32_e32 v31, v31, v23
	v_mul_f32_e32 v24, v24, v16
	v_mul_f32_e32 v25, v25, v17
	v_mul_f32_e32 v26, v26, v18
	v_mul_f32_e32 v27, v27, v19
	v_cvt_pk_bf16_f32 v20, v28, v29
	v_cvt_pk_bf16_f32 v21, v30, v31
	v_cvt_pk_bf16_f32 v22, v24, v25
	v_cvt_pk_bf16_f32 v23, v26, v27
	global_store_dwordx4 v164, v[20:23], s[10:11]
	v_add_u32_e32 v165, 0x1e4000, v162
	v_mul_f32_e32 v12, v8, v12
	v_mul_f32_e32 v13, v9, v13
	v_mul_f32_e32 v14, v10, v14
	v_mul_f32_e32 v15, v11, v15
	v_mul_f32_e32 v0, v4, v0
	v_mul_f32_e32 v1, v5, v1
	v_mul_f32_e32 v2, v6, v2
	v_mul_f32_e32 v3, v7, v3
	v_mul_f32_e32 v8, v8, v233
	v_mul_f32_e32 v9, v9, v233
	v_mul_f32_e32 v10, v10, v233
	v_mul_f32_e32 v11, v11, v233
	v_mul_f32_e32 v4, v4, v233
	v_mul_f32_e32 v5, v5, v233
	v_mul_f32_e32 v6, v6, v233
	v_mul_f32_e32 v7, v7, v233
	v_exp_f32_e32 v8, v8
	v_exp_f32_e32 v9, v9
	v_exp_f32_e32 v10, v10
	v_exp_f32_e32 v11, v11
	v_exp_f32_e32 v4, v4
	v_exp_f32_e32 v5, v5
	v_exp_f32_e32 v6, v6
	v_exp_f32_e32 v7, v7
	v_add_f32_e32 v8, 1.0, v8
	v_add_f32_e32 v9, 1.0, v9
	v_add_f32_e32 v10, 1.0, v10
	v_add_f32_e32 v11, 1.0, v11
	v_add_f32_e32 v4, 1.0, v4
	v_add_f32_e32 v5, 1.0, v5
	v_add_f32_e32 v6, 1.0, v6
	v_add_f32_e32 v7, 1.0, v7
	v_rcp_f32_e32 v8, v8
	v_rcp_f32_e32 v9, v9
	v_rcp_f32_e32 v10, v10
	v_rcp_f32_e32 v11, v11
	v_rcp_f32_e32 v4, v4
	v_rcp_f32_e32 v5, v5
	v_rcp_f32_e32 v6, v6
	v_rcp_f32_e32 v7, v7
	v_mul_f32_e32 v12, v12, v241
	v_mul_f32_e32 v13, v13, v241
	v_mul_f32_e32 v14, v14, v241
	v_mul_f32_e32 v15, v15, v241
	v_mul_f32_e32 v0, v0, v241
	v_mul_f32_e32 v1, v1, v241
	v_mul_f32_e32 v2, v2, v241
	v_mul_f32_e32 v3, v3, v241
	v_mul_f32_e32 v12, v12, v8
	v_mul_f32_e32 v13, v13, v9
	v_mul_f32_e32 v14, v14, v10
	v_mul_f32_e32 v15, v15, v11
	v_mul_f32_e32 v0, v0, v4
	v_mul_f32_e32 v1, v1, v5
	v_mul_f32_e32 v2, v2, v6
	v_mul_f32_e32 v3, v3, v7
	v_cvt_pk_bf16_f32 v8, v12, v13
	v_cvt_pk_bf16_f32 v9, v14, v15
	v_cvt_pk_bf16_f32 v10, v0, v1
	v_cvt_pk_bf16_f32 v11, v2, v3
	global_store_dwordx4 v165, v[8:11], s[10:11]
	s_andn2_b64 vcc, exec, s[8:9]
	s_mov_b64 s[8:9], -1
	s_cbranch_vccnz .LBB0_1283
	s_and_b64 vcc, exec, s[66:67]
	s_cbranch_vccnz .LBB0_1282
	s_barrier
	s_branch .LBB0_1282

; #define LAS __attribute__((address_space(3)))
; __global__ void __launch_bounds__(NTHR, 2) fwd_megakernel(Args a_by_value) {
;     extern __shared__ __attribute__((aligned(16))) unsigned char lds_raw[];
;     LAS unsigned char* lds = (LAS unsigned char*)lds_raw;
	.amdhsa_kernel _Z14fwd_megakernel4Args
		.amdhsa_group_segment_fixed_size 0
		.amdhsa_private_segment_fixed_size 0
		.amdhsa_kernarg_size 408
		.amdhsa_user_sgpr_count 2
		.amdhsa_user_sgpr_dispatch_ptr 0
		.amdhsa_user_sgpr_queue_ptr 0
		.amdhsa_user_sgpr_kernarg_segment_ptr 1
		.amdhsa_user_sgpr_dispatch_id 0
		.amdhsa_user_sgpr_kernarg_preload_length 0
		.amdhsa_user_sgpr_kernarg_preload_offset 0
		.amdhsa_user_sgpr_private_segment_size 0
		.amdhsa_uses_dynamic_stack 0
		.amdhsa_enable_private_segment 0
		.amdhsa_system_sgpr_workgroup_id_x 1
		.amdhsa_system_sgpr_workgroup_id_y 0
		.amdhsa_system_sgpr_workgroup_id_z 0
		.amdhsa_system_sgpr_workgroup_info 0
		.amdhsa_system_vgpr_workitem_id 2
		.amdhsa_next_free_vgpr 251
		.amdhsa_next_free_sgpr 100
		.amdhsa_accum_offset 252
		.amdhsa_reserve_vcc 1
		.amdhsa_float_round_mode_32 0
		.amdhsa_float_round_mode_16_64 0
		.amdhsa_float_denorm_mode_32 3
		.amdhsa_float_denorm_mode_16_64 3
		.amdhsa_dx10_clamp 1
		.amdhsa_ieee_mode 1
		.amdhsa_fp16_overflow 0
		.amdhsa_tg_split 0
		.amdhsa_exception_fp_ieee_invalid_op 0
		.amdhsa_exception_fp_denorm_src 0
		.amdhsa_exception_fp_ieee_div_zero 0
		.amdhsa_exception_fp_ieee_overflow 0
		.amdhsa_exception_fp_ieee_underflow 0
		.amdhsa_exception_fp_ieee_inexact 0
		.amdhsa_exception_int_div_zero 0
	.end_amdhsa_kernel

; __global__ void __launch_bounds__(NTHR, 2) fwd_megakernel(Args a_by_value) {
amdhsa.kernels:
  - .agpr_count:     0
    .args:
      - .offset:         0
        .size:           152
        .value_kind:     by_value
      - .offset:         152
        .size:           4
        .value_kind:     hidden_block_count_x
      - .offset:         156
        .size:           4
        .value_kind:     hidden_block_count_y
      - .offset:         160
        .size:           4
        .value_kind:     hidden_block_count_z
      - .offset:         164
        .size:           2
        .value_kind:     hidden_group_size_x
      - .offset:         166
        .size:           2
        .value_kind:     hidden_group_size_y
      - .offset:         168
        .size:           2
        .value_kind:     hidden_group_size_z
      - .offset:         170
        .size:           2
        .value_kind:     hidden_remainder_x
      - .offset:         172
        .size:           2
        .value_kind:     hidden_remainder_y
      - .offset:         174
        .size:           2
        .value_kind:     hidden_remainder_z
      - .offset:         192
        .size:           8
        .value_kind:     hidden_global_offset_x
      - .offset:         200
        .size:           8
        .value_kind:     hidden_global_offset_y
      - .offset:         208
        .size:           8
        .value_kind:     hidden_global_offset_z
      - .offset:         216
        .size:           2
        .value_kind:     hidden_grid_dims
      - .offset:         240
        .size:           8
        .value_kind:     hidden_multigrid_sync_arg
      - .offset:         272
        .size:           4
        .value_kind:     hidden_dynamic_lds_size
    .group_segment_fixed_size: 0
    .kernarg_segment_align: 8
    .kernarg_segment_size: 408
    .language:       OpenCL C
    .language_version:
      - 2
      - 0
    .max_flat_workgroup_size: 512
    .name:           _Z14fwd_megakernel4Args
    .private_segment_fixed_size: 0
    .sgpr_count:     106
    .sgpr_spill_count: 16
    .symbol:         _Z14fwd_megakernel4Args.kd
    .uniform_work_group_size: 1
    .uses_dynamic_stack: false
    .vgpr_count:     251
    .vgpr_spill_count: 0
    .wavefront_size: 64
